# attention loop: mid-iteration vmcnt(0) relaxed to a counted wait, next-row q/gate prefetch now waited at its first use
# speedup vs baseline: 1.0081x; 1.0081x over previous
.LBB0_772:
	s_or_b64 exec, exec, s[0:1]
	v_add_u32_e32 v28, s14, v63
	v_pk_mul_f32 v[22:23], v[22:23], v[26:27] op_sel_hi:[1,0]
	v_lshlrev_b32_e32 v30, 16, v92
	v_and_b32_e32 v31, 0xffff0000, v92
	s_waitcnt lgkmcnt(0)
	v_ashrrev_i32_e32 v29, 31, v28
	v_pk_mul_f32 v[22:23], v[22:23], v[30:31]
	v_pk_mul_f32 v[24:25], v[24:25], v[26:27] op_sel_hi:[1,0]
	v_lshlrev_b32_e32 v30, 16, v93
	v_and_b32_e32 v31, 0xffff0000, v93
	v_lshlrev_b64 v[28:29], 12, v[28:29]
	v_pk_mul_f32 v[24:25], v[24:25], v[30:31]
	v_cvt_pk_bf16_f32 v22, v22, v23
	v_cvt_pk_bf16_f32 v23, v24, v25
	v_lshl_add_u64 v[24:25], v[74:75], 0, v[28:29]
	global_store_dwordx2 v[24:25], v[22:23], off
	v_pk_mul_f32 v[18:19], v[18:19], v[26:27] op_sel_hi:[1,0]
	v_lshlrev_b32_e32 v22, 16, v90
	v_and_b32_e32 v23, 0xffff0000, v90
	v_pk_mul_f32 v[18:19], v[18:19], v[22:23]
	v_pk_mul_f32 v[20:21], v[20:21], v[26:27] op_sel_hi:[1,0]
	v_lshlrev_b32_e32 v22, 16, v91
	v_and_b32_e32 v23, 0xffff0000, v91
	v_pk_mul_f32 v[20:21], v[20:21], v[22:23]
	v_cvt_pk_bf16_f32 v18, v18, v19
	v_cvt_pk_bf16_f32 v19, v20, v21
	global_store_dwordx2 v[24:25], v[18:19], off offset:32
	v_pk_mul_f32 v[14:15], v[14:15], v[26:27] op_sel_hi:[1,0]
	v_lshlrev_b32_e32 v18, 16, v84
	v_and_b32_e32 v19, 0xffff0000, v84
	v_pk_mul_f32 v[14:15], v[14:15], v[18:19]
	v_pk_mul_f32 v[16:17], v[16:17], v[26:27] op_sel_hi:[1,0]
	v_lshlrev_b32_e32 v18, 16, v85
	v_and_b32_e32 v19, 0xffff0000, v85
	v_pk_mul_f32 v[16:17], v[16:17], v[18:19]
	v_cvt_pk_bf16_f32 v14, v14, v15
	v_cvt_pk_bf16_f32 v15, v16, v17
	global_store_dwordx2 v[24:25], v[14:15], off offset:64
	v_pk_mul_f32 v[10:11], v[10:11], v[26:27] op_sel_hi:[1,0]
	v_lshlrev_b32_e32 v14, 16, v76
	v_and_b32_e32 v15, 0xffff0000, v76
	v_pk_mul_f32 v[10:11], v[10:11], v[14:15]
	v_pk_mul_f32 v[12:13], v[12:13], v[26:27] op_sel_hi:[1,0]
	v_lshlrev_b32_e32 v14, 16, v77
	v_and_b32_e32 v15, 0xffff0000, v77
	v_pk_mul_f32 v[12:13], v[12:13], v[14:15]
	s_add_i32 s39, s39, 1
	s_add_i32 s14, s14, 16
	s_waitcnt vmcnt(3)
	v_mov_b64_e32 v[52:53], v[8:9]
	v_mov_b64_e32 v[48:49], v[4:5]
	v_cvt_pk_bf16_f32 v10, v10, v11
	v_cvt_pk_bf16_f32 v11, v12, v13
	s_cmpk_lg_i32 s14, 0x80
	v_mov_b64_e32 v[92:93], v[80:81]
	v_mov_b64_e32 v[90:91], v[82:83]
	v_mov_b64_e32 v[84:85], v[86:87]
	v_mov_b64_e32 v[76:77], v[88:89]
	v_mov_b64_e32 v[50:51], v[6:7]
	v_mov_b64_e32 v[46:47], v[2:3]
	global_store_dwordx2 v[24:25], v[10:11], off offset:96
	s_cbranch_scc0 .LBB0_756

.LBB0_779:
	v_max3_f32 v38, v73, s37, v10
	v_max3_f32 v38, v38, v18, v14
	v_max3_f32 v38, v38, v22, v26
	v_max3_f32 v38, v38, v30, v34
	v_max3_f32 v38, v38, v69, v125
	s_nop 1
	v_mov_b32_dpp v39, v38 quad_perm:[1,0,3,2] row_mask:0xf bank_mask:0xf
	v_max3_f32 v44, v53, s37, v11
	v_max3_f32 v44, v44, v19, v15
	v_max3_f32 v44, v44, v23, v27
	v_max3_f32 v44, v44, v31, v35
	s_waitcnt lgkmcnt(0)
	v_max_f32_e32 v39, v39, v39
	v_max_f32_e32 v38, v38, v39
	s_nop 1
	v_mov_b32_dpp v39, v38 quad_perm:[2,3,0,1] row_mask:0xf bank_mask:0xf
	v_max3_f32 v44, v44, v67, v71
	s_nop 1
	v_mov_b32_dpp v45, v44 quad_perm:[1,0,3,2] row_mask:0xf bank_mask:0xf
	s_waitcnt lgkmcnt(0)
	v_max_f32_e32 v39, v39, v39
	v_max_f32_e32 v38, v38, v39
	s_nop 1
	v_mov_b32_dpp v39, v38 row_half_mirror row_mask:0xf bank_mask:0xf
	s_waitcnt lgkmcnt(0)
	v_max_f32_e32 v45, v45, v45
	v_max_f32_e32 v44, v44, v45
	s_nop 1
	v_mov_b32_dpp v45, v44 quad_perm:[2,3,0,1] row_mask:0xf bank_mask:0xf
	s_waitcnt lgkmcnt(0)
	v_max_f32_e32 v39, v39, v39
	v_max_f32_e32 v38, v38, v39
	s_nop 1
	v_mov_b32_dpp v39, v38 row_mirror row_mask:0xf bank_mask:0xf
	s_waitcnt lgkmcnt(0)
	v_max_f32_e32 v45, v45, v45
	v_max_f32_e32 v44, v44, v45
	s_nop 1
	v_mov_b32_dpp v45, v44 row_half_mirror row_mask:0xf bank_mask:0xf
	s_waitcnt vmcnt(6) lgkmcnt(0)
	v_max3_f32 v38, v38, v39, v65
	v_sub_f32_e32 v39, v73, v38
	v_sub_f32_e32 v10, v10, v38
	v_mul_f32_e32 v39, 0x3fb8aa3b, v39
	v_sub_f32_e32 v18, v18, v38
	v_mul_f32_e32 v10, 0x3fb8aa3b, v10
	v_exp_f32_e32 v39, v39
	v_sub_f32_e32 v14, v14, v38
	v_mul_f32_e32 v18, 0x3fb8aa3b, v18
	v_exp_f32_e32 v10, v10
	v_sub_f32_e32 v22, v22, v38
	v_mul_f32_e32 v14, 0x3fb8aa3b, v14
	v_exp_f32_e32 v18, v18
	v_sub_f32_e32 v26, v26, v38
	v_mul_f32_e32 v22, 0x3fb8aa3b, v22
	v_exp_f32_e32 v14, v14
	v_sub_f32_e32 v30, v30, v38
	v_mul_f32_e32 v26, 0x3fb8aa3b, v26
	v_exp_f32_e32 v22, v22
	v_add_f32_e32 v40, 0, v39
	v_sub_f32_e32 v34, v34, v38
	v_mul_f32_e32 v30, 0x3fb8aa3b, v30
	v_exp_f32_e32 v26, v26
	v_add_f32_e32 v40, v10, v40
	v_exp_f32_e32 v30, v30
	v_add_f32_e32 v40, v18, v40
	v_mul_f32_e32 v34, 0x3fb8aa3b, v34
	v_sub_f32_e32 v41, v69, v38
	v_add_f32_e32 v40, v14, v40
	v_exp_f32_e32 v34, v34
	v_mul_f32_e32 v41, 0x3fb8aa3b, v41
	v_sub_f32_e32 v42, v125, v38
	v_add_f32_e32 v40, v22, v40
	v_exp_f32_e32 v41, v41
	v_mul_f32_e32 v42, 0x3fb8aa3b, v42
	v_add_f32_e32 v40, v26, v40
	v_exp_f32_e32 v42, v42
	v_add_f32_e32 v40, v30, v40
	v_add_f32_e32 v40, v34, v40
	v_add_f32_e32 v40, v41, v40
	v_add_f32_e32 v40, v42, v40
	s_nop 1
	v_mov_b32_dpp v43, v40 quad_perm:[1,0,3,2] row_mask:0xf bank_mask:0xf
	s_waitcnt lgkmcnt(0)
	v_max_f32_e32 v45, v45, v45
	v_max_f32_e32 v44, v44, v45
	s_nop 1
	v_mov_b32_dpp v45, v44 row_mirror row_mask:0xf bank_mask:0xf
	v_sub_f32_e32 v38, v65, v38
	s_waitcnt lgkmcnt(0)
	v_add_f32_e32 v40, v40, v43
	s_nop 1
	v_mov_b32_dpp v43, v40 quad_perm:[2,3,0,1] row_mask:0xf bank_mask:0xf
	v_mul_f32_e32 v38, 0x3fb8aa3b, v38
	v_exp_f32_e32 v38, v38
	s_waitcnt lgkmcnt(0)
	v_add_f32_e32 v40, v40, v43
	s_nop 1
	v_mov_b32_dpp v43, v40 row_half_mirror row_mask:0xf bank_mask:0xf
	s_waitcnt lgkmcnt(0)
	v_add_f32_e32 v40, v40, v43
	s_nop 1
	v_mov_b32_dpp v43, v40 row_mirror row_mask:0xf bank_mask:0xf
	s_waitcnt lgkmcnt(0)
	v_add_f32_e32 v40, v40, v43
	v_max3_f32 v43, v44, v45, v65
	v_sub_f32_e32 v44, v53, v43
	v_mul_f32_e32 v44, 0x3fb8aa3b, v44
	v_sub_f32_e32 v11, v11, v43
	v_exp_f32_e32 v44, v44
	v_mul_f32_e32 v11, 0x3fb8aa3b, v11
	v_sub_f32_e32 v19, v19, v43
	v_exp_f32_e32 v11, v11
	v_mul_f32_e32 v19, 0x3fb8aa3b, v19
	v_sub_f32_e32 v15, v15, v43
	v_exp_f32_e32 v19, v19
	v_mul_f32_e32 v15, 0x3fb8aa3b, v15
	v_sub_f32_e32 v23, v23, v43
	v_exp_f32_e32 v15, v15
	v_mul_f32_e32 v23, 0x3fb8aa3b, v23
	v_sub_f32_e32 v27, v27, v43
	v_add_f32_e32 v45, 0, v44
	v_exp_f32_e32 v23, v23
	v_mul_f32_e32 v27, 0x3fb8aa3b, v27
	v_sub_f32_e32 v31, v31, v43
	v_add_f32_e32 v45, v11, v45
	v_exp_f32_e32 v27, v27
	v_mul_f32_e32 v31, 0x3fb8aa3b, v31
	v_sub_f32_e32 v35, v35, v43
	v_add_f32_e32 v45, v19, v45
	v_exp_f32_e32 v31, v31
	v_mul_f32_e32 v35, 0x3fb8aa3b, v35
	v_sub_f32_e32 v49, v67, v43
	v_add_f32_e32 v45, v15, v45
	v_exp_f32_e32 v35, v35
	v_mul_f32_e32 v49, 0x3fb8aa3b, v49
	v_sub_f32_e32 v53, v71, v43
	v_add_f32_e32 v45, v23, v45
	v_exp_f32_e32 v49, v49
	v_mul_f32_e32 v53, 0x3fb8aa3b, v53
	v_add_f32_e32 v45, v27, v45
	v_exp_f32_e32 v53, v53
	v_add_f32_e32 v45, v31, v45
	v_add_f32_e32 v45, v35, v45
	v_add_f32_e32 v45, v49, v45
	v_add_f32_e32 v45, v53, v45
	s_nop 1
	v_mov_b32_dpp v67, v45 quad_perm:[1,0,3,2] row_mask:0xf bank_mask:0xf
	v_max3_f32 v71, v50, s37, v12
	v_max3_f32 v71, v71, v20, v16
	v_max3_f32 v71, v71, v24, v28
	v_max3_f32 v71, v71, v32, v36
	v_max3_f32 v71, v71, v51, v52
	s_waitcnt lgkmcnt(0)
	v_add_f32_e32 v45, v45, v67
	s_nop 1
	v_mov_b32_dpp v73, v71 quad_perm:[1,0,3,2] row_mask:0xf bank_mask:0xf
	s_nop 1
	v_mov_b32_dpp v67, v45 quad_perm:[2,3,0,1] row_mask:0xf bank_mask:0xf
	v_sub_f32_e32 v43, v65, v43
	v_mul_f32_e32 v43, 0x3fb8aa3b, v43
	v_exp_f32_e32 v43, v43
	s_waitcnt lgkmcnt(0)
	v_max_f32_e32 v73, v73, v73
	s_waitcnt lgkmcnt(0)
	v_add_f32_e32 v45, v45, v67
	v_max_f32_e32 v71, v71, v73
	s_nop 1
	v_mov_b32_dpp v67, v45 row_half_mirror row_mask:0xf bank_mask:0xf
	s_nop 1
	v_mov_b32_dpp v73, v71 quad_perm:[2,3,0,1] row_mask:0xf bank_mask:0xf
	v_add_f32_e32 v38, v38, v40
	v_div_scale_f32 v40, s[0:1], v38, v38, 1.0
	s_waitcnt lgkmcnt(0)
	v_add_f32_e32 v45, v45, v67
	s_waitcnt lgkmcnt(0)
	v_max_f32_e32 v67, v73, v73
	v_max_f32_e32 v67, v71, v67
	s_nop 1
	v_mov_b32_dpp v71, v67 row_half_mirror row_mask:0xf bank_mask:0xf
	s_nop 1
	v_mov_b32_dpp v73, v45 row_mirror row_mask:0xf bank_mask:0xf
	v_rcp_f32_e32 v69, v40
	s_waitcnt lgkmcnt(0)
	v_max_f32_e32 v71, v71, v71
	v_max_f32_e32 v67, v67, v71
	s_nop 1
	v_mov_b32_dpp v71, v67 row_mirror row_mask:0xf bank_mask:0xf
	s_waitcnt lgkmcnt(0)
	v_add_f32_e32 v45, v45, v73
	v_add_f32_e32 v43, v43, v45
	v_fma_f32 v125, -v40, v69, 1.0
	v_fmac_f32_e32 v69, v125, v69
	s_waitcnt lgkmcnt(0)
	v_max3_f32 v45, v67, v71, v65
	v_sub_f32_e32 v50, v50, v45
	v_mul_f32_e32 v50, 0x3fb8aa3b, v50
	v_sub_f32_e32 v12, v12, v45
	v_exp_f32_e32 v50, v50
	v_mul_f32_e32 v12, 0x3fb8aa3b, v12
	v_sub_f32_e32 v20, v20, v45
	v_exp_f32_e32 v12, v12
	v_mul_f32_e32 v20, 0x3fb8aa3b, v20
	v_sub_f32_e32 v16, v16, v45
	v_exp_f32_e32 v20, v20
	v_mul_f32_e32 v16, 0x3fb8aa3b, v16
	v_sub_f32_e32 v24, v24, v45
	v_exp_f32_e32 v16, v16
	v_mul_f32_e32 v24, 0x3fb8aa3b, v24
	v_sub_f32_e32 v28, v28, v45
	v_add_f32_e32 v73, 0, v50
	v_exp_f32_e32 v24, v24
	v_mul_f32_e32 v28, 0x3fb8aa3b, v28
	v_sub_f32_e32 v32, v32, v45
	v_add_f32_e32 v73, v12, v73
	v_exp_f32_e32 v28, v28
	v_mul_f32_e32 v32, 0x3fb8aa3b, v32
	v_sub_f32_e32 v36, v36, v45
	v_add_f32_e32 v73, v20, v73
	v_exp_f32_e32 v32, v32
	v_mul_f32_e32 v36, 0x3fb8aa3b, v36
	v_sub_f32_e32 v51, v51, v45
	v_add_f32_e32 v73, v16, v73
	v_exp_f32_e32 v36, v36
	v_mul_f32_e32 v51, 0x3fb8aa3b, v51
	v_sub_f32_e32 v52, v52, v45
	v_add_f32_e32 v73, v24, v73
	v_exp_f32_e32 v51, v51
	v_mul_f32_e32 v52, 0x3fb8aa3b, v52
	v_add_f32_e32 v73, v28, v73
	v_exp_f32_e32 v52, v52
	v_div_scale_f32 v125, vcc, 1.0, v38, 1.0
	v_add_f32_e32 v73, v32, v73
	v_mul_f32_e32 v126, v125, v69
	v_add_f32_e32 v73, v36, v73
	v_fma_f32 v127, -v40, v126, v125
	v_add_f32_e32 v73, v51, v73
	v_fmac_f32_e32 v126, v127, v69
	v_div_scale_f32 v67, s[0:1], v43, v43, 1.0
	v_add_f32_e32 v73, v52, v73
	v_fma_f32 v40, -v40, v126, v125
	v_rcp_f32_e32 v71, v67
	s_nop 1
	v_mov_b32_dpp v125, v73 quad_perm:[1,0,3,2] row_mask:0xf bank_mask:0xf
	v_div_fmas_f32 v40, v40, v69, v126
	v_div_fixup_f32 v69, v40, v38, 1.0
	v_fma_f32 v38, -v67, v71, 1.0
	v_fmac_f32_e32 v71, v38, v71
	s_waitcnt lgkmcnt(0)
	v_add_f32_e32 v38, v73, v125
	s_nop 1
	v_mov_b32_dpp v40, v38 quad_perm:[2,3,0,1] row_mask:0xf bank_mask:0xf
	v_max3_f32 v127, v46, s37, v13
	v_max3_f32 v127, v127, v21, v17
	v_max3_f32 v127, v127, v25, v29
	v_max3_f32 v127, v127, v33, v37
	v_max3_f32 v127, v127, v47, v48
	s_waitcnt lgkmcnt(0)
	v_add_f32_e32 v38, v38, v40
	s_nop 1
	v_mov_b32_dpp v128, v127 quad_perm:[1,0,3,2] row_mask:0xf bank_mask:0xf
	v_div_scale_f32 v73, vcc, 1.0, v43, 1.0
	s_nop 1
	v_mov_b32_dpp v40, v38 row_half_mirror row_mask:0xf bank_mask:0xf
	v_mul_f32_e32 v125, v73, v71
	v_fma_f32 v126, -v67, v125, v73
	v_fmac_f32_e32 v125, v126, v71
	v_fma_f32 v67, -v67, v125, v73
	s_waitcnt lgkmcnt(0)
	v_max_f32_e32 v73, v128, v128
	s_waitcnt lgkmcnt(0)
	v_add_f32_e32 v38, v38, v40
	v_max_f32_e32 v73, v127, v73
	s_nop 1
	v_mov_b32_dpp v40, v38 row_mirror row_mask:0xf bank_mask:0xf
	s_nop 1
	v_mov_b32_dpp v126, v73 quad_perm:[2,3,0,1] row_mask:0xf bank_mask:0xf
	s_waitcnt lgkmcnt(0)
	v_add_f32_e32 v38, v38, v40
	v_sub_f32_e32 v40, v65, v45
	s_waitcnt lgkmcnt(0)
	v_max_f32_e32 v45, v126, v126
	v_max_f32_e32 v45, v73, v45
	v_mul_f32_e32 v40, 0x3fb8aa3b, v40
	s_nop 1
	v_mov_b32_dpp v73, v45 row_half_mirror row_mask:0xf bank_mask:0xf
	v_exp_f32_e32 v40, v40
	s_nop 0
	v_add_f32_e32 v130, v40, v38
	s_waitcnt lgkmcnt(0)
	v_max_f32_e32 v38, v73, v73
	v_max_f32_e32 v38, v45, v38
	s_nop 1
	v_mov_b32_dpp v40, v38 row_mirror row_mask:0xf bank_mask:0xf
	v_div_scale_f32 v131, s[0:1], v130, v130, 1.0
	v_rcp_f32_e32 v132, v131
	v_div_fmas_f32 v45, v67, v71, v125
	s_waitcnt lgkmcnt(0)
	v_max3_f32 v71, v38, v40, v65
	v_sub_f32_e32 v33, v33, v71
	v_div_fixup_f32 v67, v45, v43, 1.0
	v_fma_f32 v43, -v131, v132, 1.0
	v_mul_f32_e32 v33, 0x3fb8aa3b, v33
	v_fmac_f32_e32 v132, v43, v132
	v_exp_f32_e32 v43, v33
	v_sub_f32_e32 v33, v37, v71
	v_mul_f32_e32 v33, 0x3fb8aa3b, v33
	v_exp_f32_e32 v45, v33
	v_sub_f32_e32 v33, v47, v71
	v_sub_f32_e32 v38, v46, v71
	v_mul_f32_e32 v33, 0x3fb8aa3b, v33
	v_mul_f32_e32 v38, 0x3fb8aa3b, v38
	v_exp_f32_e32 v73, v33
	v_sub_f32_e32 v33, v48, v71
	v_exp_f32_e32 v38, v38
	v_mul_f32_e32 v33, 0x3fb8aa3b, v33
	v_sub_f32_e32 v13, v13, v71
	v_exp_f32_e32 v125, v33
	v_cvt_pk_bf16_f32 v33, v39, s0
	v_mul_f32_e32 v13, 0x3fb8aa3b, v13
	ds_write_b16 v121, v33
	v_cvt_pk_bf16_f32 v33, v44, s0
	v_exp_f32_e32 v13, v13
	ds_write_b16 v122, v33
	v_cvt_pk_bf16_f32 v33, v50, s0
	ds_write_b16 v122, v33 offset:336
	v_cvt_pk_bf16_f32 v33, v38, s0
	v_cvt_pk_bf16_f32 v10, v10, s0
	v_sub_f32_e32 v21, v21, v71
	ds_write_b16 v122, v33 offset:672
	ds_write_b16 v121, v10 offset:32
	v_cvt_pk_bf16_f32 v10, v11, s0
	v_mul_f32_e32 v21, 0x3fb8aa3b, v21
	ds_write_b16 v122, v10 offset:32
	v_cvt_pk_bf16_f32 v10, v12, s0
	v_exp_f32_e32 v21, v21
	ds_write_b16 v122, v10 offset:368
	v_cvt_pk_bf16_f32 v10, v13, s0
	ds_write_b16 v122, v10 offset:704
	v_cvt_pk_bf16_f32 v10, v18, s0
	v_sub_f32_e32 v17, v17, v71
	ds_write_b16 v121, v10 offset:64
	v_cvt_pk_bf16_f32 v10, v19, s0
	v_mul_f32_e32 v17, 0x3fb8aa3b, v17
	ds_write_b16 v122, v10 offset:64
	v_cvt_pk_bf16_f32 v10, v20, s0
	v_exp_f32_e32 v17, v17
	ds_write_b16 v122, v10 offset:400
	v_cvt_pk_bf16_f32 v10, v21, s0
	ds_write_b16 v122, v10 offset:736
	v_cvt_pk_bf16_f32 v10, v14, s0
	v_sub_f32_e32 v25, v25, v71
	ds_write_b16 v121, v10 offset:96
	v_cvt_pk_bf16_f32 v10, v15, s0
	v_mul_f32_e32 v25, 0x3fb8aa3b, v25
	ds_write_b16 v122, v10 offset:96
	v_cvt_pk_bf16_f32 v10, v16, s0
	v_exp_f32_e32 v25, v25
	ds_write_b16 v122, v10 offset:432
	v_cvt_pk_bf16_f32 v10, v17, s0
	ds_write_b16 v122, v10 offset:768
	v_cvt_pk_bf16_f32 v10, v22, s0
	v_sub_f32_e32 v29, v29, v71
	ds_write_b16 v121, v10 offset:128
	v_cvt_pk_bf16_f32 v10, v23, s0
	v_mul_f32_e32 v29, 0x3fb8aa3b, v29
	ds_write_b16 v122, v10 offset:128
	v_cvt_pk_bf16_f32 v10, v24, s0
	v_exp_f32_e32 v29, v29
	ds_write_b16 v122, v10 offset:464
	v_cvt_pk_bf16_f32 v10, v25, s0
	ds_write_b16 v122, v10 offset:800
	v_cvt_pk_bf16_f32 v10, v26, s0
	ds_write_b16 v121, v10 offset:160
	v_cvt_pk_bf16_f32 v10, v27, s0
	ds_write_b16 v122, v10 offset:160
	v_cvt_pk_bf16_f32 v10, v28, s0
	ds_write_b16 v122, v10 offset:496
	v_cvt_pk_bf16_f32 v10, v29, s0
	ds_write_b16 v122, v10 offset:832
	v_cvt_pk_bf16_f32 v10, v30, s0
	ds_write_b16 v121, v10 offset:192
	v_cvt_pk_bf16_f32 v10, v31, s0
	ds_write_b16 v122, v10 offset:192
	v_cvt_pk_bf16_f32 v10, v32, s0
	ds_write_b16 v122, v10 offset:528
	v_cvt_pk_bf16_f32 v10, v43, s0
	ds_write_b16 v122, v10 offset:864
	v_cvt_pk_bf16_f32 v10, v34, s0
	ds_write_b16 v121, v10 offset:224
	v_cvt_pk_bf16_f32 v10, v35, s0
	ds_write_b16 v122, v10 offset:224
	v_cvt_pk_bf16_f32 v10, v36, s0
	ds_write_b16 v122, v10 offset:560
	v_cvt_pk_bf16_f32 v10, v45, s0
	ds_write_b16 v122, v10 offset:896
	v_cvt_pk_bf16_f32 v10, v41, s0
	ds_write_b16 v121, v10 offset:256
	v_cvt_pk_bf16_f32 v10, v49, s0
	ds_write_b16 v122, v10 offset:256
	v_cvt_pk_bf16_f32 v10, v51, s0
	ds_write_b16 v122, v10 offset:592
	v_cvt_pk_bf16_f32 v10, v73, s0
	ds_write_b16 v122, v10 offset:928
	v_cvt_pk_bf16_f32 v10, v42, s0
	ds_write_b16 v121, v10 offset:288
	v_cvt_pk_bf16_f32 v10, v53, s0
	v_add_f32_e32 v40, 0, v38
	ds_write_b16 v122, v10 offset:288
	v_cvt_pk_bf16_f32 v10, v52, s0
	v_add_f32_e32 v40, v13, v40
	ds_write_b16 v122, v10 offset:624
	v_cvt_pk_bf16_f32 v10, v125, s0
	v_add_f32_e32 v40, v21, v40
	ds_write_b16 v122, v10 offset:960
	v_add_u32_e32 v10, s40, v56
	v_lshl_add_u32 v133, v10, 1, v112
	v_add_f32_e32 v14, v17, v40
	ds_read_b128 v[10:13], v133 offset:36864
	v_add_f32_e32 v22, v25, v14
	v_add_f32_e32 v34, v29, v22
	v_add_f32_e32 v42, v43, v34
	v_add_f32_e32 v50, v45, v42
	ds_read_b128 v[14:17], v123
	ds_read_b128 v[18:21], v133 offset:45312
	v_add_f32_e32 v50, v73, v50
	ds_read_b128 v[22:25], v133 offset:53760
	ds_read_b128 v[26:29], v123 offset:64
	ds_read_b128 v[30:33], v123 offset:256
	ds_read_b128 v[34:37], v133 offset:62208
	ds_read_b128 v[38:41], v133 offset:45376
	v_add_f32_e32 v73, v125, v50
	s_nop 1
	v_mov_b32_dpp v125, v73 quad_perm:[1,0,3,2] row_mask:0xf bank_mask:0xf
	s_waitcnt lgkmcnt(6)
	v_mfma_f32_16x16x32_bf16 v[10:13], v[10:13], v[14:17], 0
	ds_read_b128 v[42:45], v133 offset:36928
	ds_read_b128 v[46:49], v133 offset:45568
	ds_read_b128 v[50:53], v133 offset:62272
	v_sub_f32_e32 v71, v65, v71
	s_waitcnt lgkmcnt(8)
	v_mfma_f32_16x16x32_bf16 v[18:21], v[18:21], v[14:17], 0
	s_waitcnt lgkmcnt(3)
	v_add_f32_e32 v73, v73, v125
	s_nop 1
	v_mov_b32_dpp v125, v73 quad_perm:[2,3,0,1] row_mask:0xf bank_mask:0xf
	v_div_scale_f32 v134, vcc, 1.0, v130, 1.0
	v_mfma_f32_16x16x32_bf16 v[22:25], v[22:25], v[14:17], 0
	v_mul_f32_e32 v135, v134, v132
	s_waitcnt lgkmcnt(0)
	v_add_f32_e32 v73, v73, v125
	s_nop 1
	v_mov_b32_dpp v125, v73 row_half_mirror row_mask:0xf bank_mask:0xf
	v_mfma_f32_16x16x32_bf16 v[14:17], v[34:37], v[14:17], 0
	ds_read_b128 v[34:37], v133 offset:53824
	ds_read_b128 v[126:129], v133 offset:36992
	v_fma_f32 v136, -v131, v135, v134
	v_fmac_f32_e32 v135, v136, v132
	v_mfma_f32_16x16x32_bf16 v[10:13], v[42:45], v[26:29], v[10:13]
	s_waitcnt lgkmcnt(2)
	v_add_f32_e32 v73, v73, v125
	s_nop 1
	v_mov_b32_dpp v125, v73 row_mirror row_mask:0xf bank_mask:0xf
	v_fma_f32 v131, -v131, v135, v134
	v_mfma_f32_16x16x32_bf16 v[18:21], v[38:41], v[26:29], v[18:21]
	ds_read_b128 v[38:41], v133 offset:53888
	s_waitcnt lgkmcnt(2)
	v_mfma_f32_16x16x32_bf16 v[22:25], v[34:37], v[26:29], v[22:25]
	ds_read_b128 v[34:37], v123 offset:128
	ds_read_b128 v[42:45], v133 offset:45440
	v_mfma_f32_16x16x32_bf16 v[14:17], v[50:53], v[26:29], v[14:17]
	ds_read_b128 v[26:29], v123 offset:192
	s_waitcnt lgkmcnt(2)
	v_mfma_f32_16x16x32_bf16 v[10:13], v[126:129], v[34:37], v[10:13]
	ds_read_b128 v[50:53], v133 offset:62336
	ds_read_b128 v[126:129], v133 offset:45504
	s_waitcnt lgkmcnt(3)
	v_mfma_f32_16x16x32_bf16 v[18:21], v[42:45], v[34:37], v[18:21]
	ds_read_b128 v[42:45], v133 offset:37056
	v_mfma_f32_16x16x32_bf16 v[22:25], v[38:41], v[34:37], v[22:25]
	ds_read_b128 v[38:41], v133 offset:62400
	s_waitcnt lgkmcnt(3)
	v_mfma_f32_16x16x32_bf16 v[14:17], v[50:53], v[34:37], v[14:17]
	v_mul_f32_e32 v34, 0x3fb8aa3b, v71
	v_exp_f32_e32 v50, v34
	ds_read_b128 v[34:37], v133 offset:37120
	s_waitcnt lgkmcnt(2)
	v_mfma_f32_16x16x32_bf16 v[10:13], v[42:45], v[26:29], v[10:13]
	ds_read_b128 v[42:45], v133 offset:53952
	v_add_f32_e32 v51, v73, v125
	v_add_f32_e32 v73, v50, v51
	v_div_scale_f32 v125, s[0:1], v73, v73, 1.0
	v_mfma_f32_16x16x32_bf16 v[18:21], v[126:129], v[26:29], v[18:21]
	v_rcp_f32_e32 v126, v125
	ds_read_b128 v[50:53], v133 offset:54016
	v_div_fmas_f32 v71, v131, v132, v135
	s_waitcnt lgkmcnt(1)
	v_mfma_f32_16x16x32_bf16 v[42:45], v[42:45], v[26:29], v[22:25]
	v_div_fixup_f32 v71, v71, v130, 1.0
	s_nop 1
	v_fma_f32 v22, -v125, v126, 1.0
	v_fmac_f32_e32 v126, v22, v126
	v_mfma_f32_16x16x32_bf16 v[38:41], v[38:41], v[26:29], v[14:17]
	ds_bpermute_b32 v26, v102, v69
	ds_bpermute_b32 v27, v102, v67
	ds_bpermute_b32 v28, v102, v71
	v_div_scale_f32 v14, vcc, 1.0, v73, 1.0
	v_mul_f32_e32 v15, v14, v126
	v_mfma_f32_16x16x32_bf16 v[22:25], v[34:37], v[30:33], v[10:13]
	s_nop 2
	v_fma_f32 v10, -v125, v15, v14
	v_fmac_f32_e32 v15, v10, v126
	ds_read_b128 v[10:13], v133 offset:62464
	v_fma_f32 v14, -v125, v15, v14
	v_div_fmas_f32 v14, v14, v126, v15
	v_div_fixup_f32 v29, v14, v73, 1.0
	ds_bpermute_b32 v29, v102, v29
	v_mfma_f32_16x16x32_bf16 v[18:21], v[46:49], v[30:33], v[18:21]
	v_cmp_lt_i32_e32 vcc, 0, v103
	s_waitcnt lgkmcnt(5)
	v_mfma_f32_16x16x32_bf16 v[14:17], v[50:53], v[30:33], v[42:45]
	s_waitcnt lgkmcnt(1)
	v_mfma_f32_16x16x32_bf16 v[10:13], v[10:13], v[30:33], v[38:41]
	s_and_saveexec_b64 s[0:1], vcc
	s_cbranch_execz .LBB0_772
	v_cmp_ne_u32_e32 vcc, 1, v103
	s_and_saveexec_b64 s[22:23], vcc
	s_xor_b64 s[22:23], exec, s[22:23]
	s_cbranch_execz .LBB0_782
	s_waitcnt lgkmcnt(0)
	v_cndmask_b32_e64 v26, v29, v28, s[4:5]
